# rwkv2 role 1: beta raw-token LDS reads and gamma norm/bonus LDS reads hoisted to the segment heads
# baseline (speedup 1.0000x reference)
; __device__ unsigned long long rwkv2_phase(const Params& p, unsigned char* smem) {
;     ...
;                 if (prep) {
;                     float kkv[4], a_[4], eP[4], eTi[4];
;                     f32x4 accW = {0.f, 0.f, 0.f, 0.f}, accA = {0.f, 0.f, 0.f, 0.f};
; #pragma unroll
;                     for (int ks = 0; ks < 3; ++ks) { const bf16x8 afw = *(const bf16x8*)(twa + l15 * 104 + 32 * ks + 8 * lq), afa = *(const bf16x8*)(twa + (16 + l15) * 104 + 32 * ks + 8 * lq);
;                         const bf16x8 bwf = *(const bf16x8*)(W2t + k * 104 + 32 * ks + 8 * lq), baf = *(const bf16x8*)(A2t + k * 104 + 32 * ks + 8 * lq);
;                         accW = MFMA16(afw, bwf, accW); accA = MFMA16(afa, baf, accA); }
;                     float ld[4]; f32x4 cum = {0.f, 0.f, 0.f, 0.f};
; #pragma unroll
;                     for (int r = 0; r < 4; ++r) ld[r] = -0.60653066f * fsigmoid(w0k + accW[r]);
; #pragma unroll
;                     for (int r = 0; r < 4; ++r) cum = __builtin_amdgcn_mfma_f32_16x16x4f32((4 * lq + r <= l15) ? 1.0f : 0.0f, ld[r], cum, 0, 0, 0);
;                     float kmq[4], vq[4];
; #pragma unroll
;                     for (int r = 0; r < 4; ++r) { const int t = 4 * lq + r;
;                         const float rr = bf2f(raw[(0 * 17 + t + 1) * 64 + k]), rp_ = bf2f(raw[(0 * 17 + t) * 64 + k]);
;                         const float kr_ = bf2f(raw[(1 * 17 + t + 1) * 64 + k]), kp = bf2f(raw[(1 * 17 + t) * 64 + k]);
;                         const float vr = bf2f(raw[(2 * 17 + t + 1) * 64 + k]), vp = bf2f(raw[(2 * 17 + t) * 64 + k]);
;                         const float r_ = rr + (rp_ - rr) * mu_r, kx0 = kr_ + (kp - kr_) * mu_k, v_ = vr + (vp - vr) * mu_v;
;                         a_[r] = fsigmoid(a0k + accA[r]); kkv[r] = kx0 * kkk;
;                         const float kmod = kx0 * (1.0f + (a_[r] - 1.0f) * kak);
;                         const float eT = __expf(cum[r]); eTi[r] = __builtin_amdgcn_rcpf(eT); eP[r] = __expf(cum[r] - ld[r]);
;                         const float ssp = row16_sum(kkv[r] * kkv[r]), bop = row16_sum(r_ * kmod * rkk);
;                         if (l15 == 0) { ssP[t * 4 + w4] = ssp; bonP[t * 4 + w4] = bop; }
;                         Rt[t * 72 + k] = f2bf(r_ * eT); kmq[r] = kmod * eTi[r]; Kt[t * 72 + k] = f2bf(kmq[r]);
;                         Vf[t * 64 + k] = v_; vq[r] = v_;
.LBB0_981:
	s_bitcmp1_b32 s31, 0
	s_cselect_b32 s26, 0x2400, 0
	s_add_i32 s68, s26, 0
	s_mul_i32 s26, s31, 0xaaab
	s_lshr_b32 s26, s26, 17
	s_mul_i32 s26, s26, 3
	s_sub_i32 s26, s31, s26
	s_mulk_i32 s26, 0x2940
	s_and_b32 s26, s26, 0xffc0
	s_waitcnt lgkmcnt(0)
	s_barrier
	s_add_i32 s33, s26, 0
	v_cndmask_b32_e64 v42, 0, 1, s[28:29]
	v_and_b32_e32 v75, 15, v73
	v_ashrrev_i32_e32 v74, 4, v73
	s_add_i32 s62, s33, 0xe380
	v_cmp_ne_u32_e64 s[26:27], 1, v42
	s_andn2_b64 vcc, exec, s[28:29]
	s_cbranch_vccnz .LBB0_993
	v_lshl_add_u32 v204, v74, 9, v152
	v_lshl_or_b32 v205, v74, 8, v102
	v_lshl_add_u32 v205, v205, 1, 0
	ds_read_u16 v180, v204 offset:26752
	ds_read_u16 v181, v205 offset:26624
	ds_read_u16 v182, v204 offset:28928
	ds_read_u16 v183, v204 offset:31104
	ds_read_u16 v184, v204 offset:30976
	ds_read_u16 v185, v204 offset:28800
	ds_read_u16 v186, v204 offset:26880
	ds_read_u16 v187, v205 offset:26752
	ds_read_u16 v188, v204 offset:29056
	ds_read_u16 v189, v204 offset:31232
	ds_read_u16 v190, v204 offset:31104
	ds_read_u16 v191, v204 offset:28928
	ds_read_u16 v192, v204 offset:27008
	ds_read_u16 v193, v205 offset:26880
	ds_read_u16 v194, v204 offset:29184
	ds_read_u16 v195, v204 offset:31360
	ds_read_u16 v196, v204 offset:31232
	ds_read_u16 v197, v204 offset:29056
	ds_read_u16 v198, v204 offset:27136
	ds_read_u16 v199, v205 offset:27008
	ds_read_u16 v200, v204 offset:29312
	ds_read_u16 v201, v204 offset:31488
	ds_read_u16 v202, v204 offset:31360
	ds_read_u16 v203, v204 offset:29184
	v_mul_u32_u24_e32 v42, 0xd0, v75
	v_lshlrev_b32_e32 v46, 4, v74
	v_add3_u32 v96, 0, v42, v46
	ds_read_b128 v[42:45], v96 offset:33152
	v_add_u32_e32 v100, v131, v46
	ds_read_b128 v[46:49], v100
	ds_read_b128 v[56:59], v96 offset:33216
	ds_read_b128 v[76:79], v100 offset:64
	s_waitcnt lgkmcnt(2)
	v_mfma_f32_16x16x32_bf16 v[42:45], v[42:45], v[46:49], 0
	ds_read_b128 v[46:49], v96 offset:33280
	ds_read_b128 v[80:83], v100 offset:128
	ds_read_b128 v[84:87], v96 offset:36480
	ds_read_b128 v[88:91], v100 offset:13312
	s_waitcnt lgkmcnt(4)
	v_mfma_f32_16x16x32_bf16 v[42:45], v[56:59], v[76:79], v[42:45]
	v_lshlrev_b32_e32 v58, 2, v74
	v_sub_u32_e32 v56, v75, v58
	v_cmp_gt_i32_e32 vcc, 0, v56
	s_waitcnt lgkmcnt(2)
	v_mfma_f32_16x16x32_bf16 v[42:45], v[46:49], v[80:83], v[42:45]
	v_cndmask_b32_e64 v46, 1.0, 0, vcc
	v_cmp_gt_i32_e32 vcc, 1, v56
	s_waitcnt lgkmcnt(0)
	v_mfma_f32_16x16x32_bf16 v[82:85], v[84:87], v[88:91], 0
	v_mov_b32_e32 v87, 0
	s_waitcnt vmcnt(4)
	s_nop 1
	v_add_f32_e32 v42, v62, v42
	v_mul_f32_e32 v42, 0xbfb8aa3b, v42
	v_exp_f32_e32 v42, v42
	v_add_f32_e32 v43, v62, v43
	v_mul_f32_e32 v43, 0xbfb8aa3b, v43
	v_exp_f32_e32 v43, v43
	v_add_f32_e32 v42, 1.0, v42
	v_rcp_f32_e32 v42, v42
	v_add_f32_e32 v44, v62, v44
	v_add_f32_e32 v43, 1.0, v43
	v_rcp_f32_e32 v43, v43
	v_mul_f32_e32 v76, 0xbf1b4598, v42
	v_cndmask_b32_e64 v42, 1.0, 0, vcc
	v_mul_f32_e32 v44, 0xbfb8aa3b, v44
	v_mfma_f32_16x16x4_f32 v[46:49], v46, v76, 0
	v_exp_f32_e32 v44, v44
	v_mul_f32_e32 v57, 0xbf1b4598, v43
	v_cmp_gt_i32_e32 vcc, 2, v56
	v_add_f32_e32 v43, 1.0, v44
	v_rcp_f32_e32 v43, v43
	v_mfma_f32_16x16x4_f32 v[46:49], v42, v57, v[46:49]
	v_cndmask_b32_e64 v42, 1.0, 0, vcc
	v_mul_f32_e32 v77, 0xbf1b4598, v43
	v_cmp_gt_i32_e32 vcc, 3, v56
	s_nop 1
	v_cndmask_b32_e64 v56, 1.0, 0, vcc
	v_cmp_eq_u32_e32 vcc, 0, v75
	v_mfma_f32_16x16x4_f32 v[78:81], v42, v77, v[46:49]
	s_nop 1
	ds_read_b128 v[46:49], v96 offset:36544
	ds_read_b128 v[92:95], v100 offset:13376
	ds_read_b128 v[96:99], v96 offset:36608
	v_add_f32_e32 v42, v62, v45
	v_mul_f32_e32 v42, 0xbfb8aa3b, v42
	v_exp_f32_e32 v59, v42
	ds_read_b128 v[42:45], v100 offset:13440
	v_add_f32_e32 v59, 1.0, v59
	s_waitcnt lgkmcnt(2)
	v_mfma_f32_16x16x32_bf16 v[46:49], v[46:49], v[92:95], v[82:85]
	s_waitcnt lgkmcnt(0)
	v_mfma_f32_16x16x32_bf16 v[46:49], v[96:99], v[42:45], v[46:49]
	v_rcp_f32_e32 v42, v59
	s_nop 0
	v_mul_f32_e32 v59, 0xbf1b4598, v42
	s_nop 1
	v_mfma_f32_16x16x4_f32 v[42:45], v56, v59, v[78:81]
	v_lshl_or_b32 v56, v74, 8, v102
	v_lshl_add_u32 v78, v74, 9, v152
	v_lshl_add_u32 v79, v56, 1, 0
	s_waitcnt vmcnt(3)
	v_add_f32_e32 v46, v63, v46
	s_waitcnt lgkmcnt(0)
	v_mov_b32_e32 v81, v180
	v_mov_b32_e32 v79, v181
	v_mov_b32_e32 v83, v182
	v_mov_b32_e32 v80, v183
	v_mov_b32_e32 v82, v184
	v_mov_b32_e32 v78, v185
	v_mul_f32_e32 v46, 0xbfb8aa3b, v46
	v_exp_f32_e32 v46, v46
	s_waitcnt lgkmcnt(5)
	v_lshlrev_b32_e32 v81, 16, v81
	s_waitcnt lgkmcnt(4)
	v_lshlrev_b32_e32 v79, 16, v79
	s_waitcnt lgkmcnt(0)
	v_lshlrev_b32_e32 v84, 16, v78
	v_sub_f32_e32 v78, v79, v81
	v_add_f32_e32 v46, 1.0, v46
	v_fmac_f32_e32 v81, v3, v78
	v_rcp_f32_e32 v78, v46
	v_lshlrev_b32_e32 v83, 16, v83
	v_sub_f32_e32 v46, v84, v83
	v_fmac_f32_e32 v83, v60, v46
	v_add_f32_e32 v46, -1.0, v78
	s_waitcnt vmcnt(1)
	v_fma_f32 v46, v65, v46, 1.0
	v_mul_f32_e32 v79, v64, v83
	v_mul_f32_e32 v83, v46, v83
	v_mul_f32_e32 v85, v81, v83
	v_mul_f32_e32 v46, v79, v79
	v_mov_b32_e32 v84, 0
	s_waitcnt vmcnt(0)
	v_mul_f32_e32 v86, v66, v85
	v_mov_b32_dpp v84, v46 quad_perm:[1,0,3,2] row_mask:0xf bank_mask:0xf
	s_nop 0
	v_mov_b32_dpp v87, v86 quad_perm:[1,0,3,2] row_mask:0xf bank_mask:0xf
	v_fmac_f32_e32 v84, v79, v79
	v_fmac_f32_e32 v87, v66, v85
	v_mov_b32_e32 v86, 0
	v_add_f32_dpp v46, v84, v84 quad_perm:[2,3,0,1] row_mask:0xf bank_mask:0xf bound_ctrl:1
	v_add_f32_dpp v85, v87, v87 quad_perm:[2,3,0,1] row_mask:0xf bank_mask:0xf bound_ctrl:1
	v_mov_b32_e32 v84, 0
	v_add_f32_dpp v46, v46, v46 row_half_mirror row_mask:0xf bank_mask:0xf bound_ctrl:1
	v_add_f32_dpp v85, v85, v85 row_half_mirror row_mask:0xf bank_mask:0xf bound_ctrl:1
	s_nop 0
	v_mov_b32_dpp v84, v46 row_mirror row_mask:0xf bank_mask:0xf
	v_mov_b32_dpp v86, v85 row_mirror row_mask:0xf bank_mask:0xf
	s_and_saveexec_b64 s[28:29], vcc
	s_cbranch_execz .LBB0_984
	v_add_f32_e32 v46, v46, v84
	v_add_f32_e32 v84, v85, v86
	v_or_b32_e32 v85, s88, v73
	v_lshl_add_u32 v85, v85, 2, 0
	v_add_u32_e32 v86, 0x19b40, v85
	v_add_u32_e32 v85, 0x19c40, v85
	ds_write_b32 v86, v46
	ds_write_b32 v85, v84
; __device__ __forceinline__ u16 f2bf(float f) { return (u16)(pk2(f, 0.f) & 0xffffu); }
; __device__ __forceinline__ float bf2f(u16 v) { return __uint_as_float(((unsigned)v) << 16); }
; __device__ __forceinline__ float fsigmoid(float x) { return __builtin_amdgcn_rcpf(1.0f + __expf(-x)); }
; __device__ __forceinline__ float row16_sum(float v) { v += dppf<0xB1>(v); v += dppf<0x4E>(v); v += dppf<0x141>(v); v += dppf<0x140>(v); return v; }
; __device__ unsigned long long rwkv2_phase(const Params& p, unsigned char* smem) {
;     ...
;                     float kmq[4], vq[4];
; #pragma unroll
;                     for (int r = 0; r < 4; ++r) { const int t = 4 * lq + r;
;                         const float rr = bf2f(raw[(0 * 17 + t + 1) * 64 + k]), rp_ = bf2f(raw[(0 * 17 + t) * 64 + k]);
;                         const float kr_ = bf2f(raw[(1 * 17 + t + 1) * 64 + k]), kp = bf2f(raw[(1 * 17 + t) * 64 + k]);
;                         const float vr = bf2f(raw[(2 * 17 + t + 1) * 64 + k]), vp = bf2f(raw[(2 * 17 + t) * 64 + k]);
;                         const float r_ = rr + (rp_ - rr) * mu_r, kx0 = kr_ + (kp - kr_) * mu_k, v_ = vr + (vp - vr) * mu_v;
;                         a_[r] = fsigmoid(a0k + accA[r]); kkv[r] = kx0 * kkk;
;                         const float kmod = kx0 * (1.0f + (a_[r] - 1.0f) * kak);
;                         const float eT = __expf(cum[r]); eTi[r] = __builtin_amdgcn_rcpf(eT); eP[r] = __expf(cum[r] - ld[r]);
;                         const float ssp = row16_sum(kkv[r] * kkv[r]), bop = row16_sum(r_ * kmod * rkk);
;                         if (l15 == 0) { ssP[t * 4 + w4] = ssp; bonP[t * 4 + w4] = bop; }
;                         Rt[t * 72 + k] = f2bf(r_ * eT); kmq[r] = kmod * eTi[r]; Kt[t * 72 + k] = f2bf(kmq[r]);
;                         Vf[t * 64 + k] = v_; vq[r] = v_;
;                         au[r] = -kkv[r] * eP[r]; bu[r] = kkv[r] * a_[r] * eTi[r];
;                         if (t == 15) W15[k] = eT; }
.LBB0_984:
	s_or_b64 exec, exec, s[28:29]
	v_mul_f32_e32 v46, 0x3fb8aa3b, v42
	v_exp_f32_e32 v84, v46
	v_lshlrev_b32_e32 v80, 16, v80
	v_lshlrev_b32_e32 v46, 16, v82
	v_sub_f32_e32 v46, v46, v80
	v_fmac_f32_e32 v80, v61, v46
	v_rcp_f32_e32 v46, v84
	v_add_f32_e32 v47, v63, v47
	v_mul_f32_e32 v81, v84, v81
	v_mad_u64_u32 v[84:85], s[28:29], v74, s50, v[102:103]
	v_mul_f32_e32 v47, 0xbfb8aa3b, v47
	v_lshl_add_u32 v82, v84, 1, s68
	v_or_b32_e32 v84, 1, v58
	v_exp_f32_e32 v47, v47
	v_cvt_pk_bf16_f32 v81, v81, v2
	v_lshl_add_u32 v56, v56, 2, s33
	v_lshl_or_b32 v86, v84, 6, v102
	ds_write_b16 v82, v81 offset:42112
	v_mul_f32_e32 v81, v46, v83
	v_cvt_pk_bf16_f32 v83, v81, v2
	ds_write_b16 v82, v83 offset:46720
	ds_write_b32 v56, v80 offset:58240
	v_lshl_add_u32 v82, v84, 7, v152
	v_lshl_add_u32 v56, v86, 1, 0
	v_mov_b32_e32 v85, v186
	v_mov_b32_e32 v87, v187
	v_mov_b32_e32 v88, v188
	v_mov_b32_e32 v83, v189
	v_mov_b32_e32 v56, v190
	v_mov_b32_e32 v82, v191
	v_add_f32_e32 v47, 1.0, v47
	v_rcp_f32_e32 v47, v47
	s_waitcnt lgkmcnt(5)
	v_lshlrev_b32_e32 v85, 16, v85
	s_waitcnt lgkmcnt(4)
	v_lshlrev_b32_e32 v87, 16, v87
	s_waitcnt lgkmcnt(3)
	v_lshlrev_b32_e32 v88, 16, v88
	s_waitcnt lgkmcnt(0)
	v_lshlrev_b32_e32 v82, 16, v82
	v_sub_f32_e32 v87, v87, v85
	v_fmac_f32_e32 v85, v3, v87
	v_sub_f32_e32 v82, v82, v88
	v_add_f32_e32 v87, -1.0, v47
	v_fmac_f32_e32 v88, v60, v82
	v_fma_f32 v87, v65, v87, 1.0
	v_mul_f32_e32 v87, v87, v88
	v_mul_f32_e32 v82, v64, v88
	v_mul_f32_e32 v90, v85, v87
	v_mul_f32_e32 v88, v82, v82
	v_mov_b32_e32 v89, 0
	v_mul_f32_e32 v91, v66, v90
	v_mov_b32_e32 v92, 0
	v_mov_b32_dpp v89, v88 quad_perm:[1,0,3,2] row_mask:0xf bank_mask:0xf
	v_fmac_f32_e32 v89, v82, v82
	v_mov_b32_dpp v92, v91 quad_perm:[1,0,3,2] row_mask:0xf bank_mask:0xf
	v_fmac_f32_e32 v92, v66, v90
	v_add_f32_dpp v88, v89, v89 quad_perm:[2,3,0,1] row_mask:0xf bank_mask:0xf bound_ctrl:1
	v_mov_b32_e32 v89, 0
	v_add_f32_dpp v90, v92, v92 quad_perm:[2,3,0,1] row_mask:0xf bank_mask:0xf bound_ctrl:1
	v_add_f32_dpp v88, v88, v88 row_half_mirror row_mask:0xf bank_mask:0xf bound_ctrl:1
	v_mov_b32_e32 v91, 0
	v_add_f32_dpp v90, v90, v90 row_half_mirror row_mask:0xf bank_mask:0xf bound_ctrl:1
	v_mov_b32_dpp v89, v88 row_mirror row_mask:0xf bank_mask:0xf
	s_nop 0
	v_mov_b32_dpp v91, v90 row_mirror row_mask:0xf bank_mask:0xf
	s_and_saveexec_b64 s[28:29], vcc
	s_cbranch_execz .LBB0_986
	s_lshl_b32 s56, s88, 2
	v_lshl_or_b32 v92, v84, 4, s56
	v_add_u32_e32 v92, 0, v92
	v_add_u32_e32 v93, 0x19c40, v92
	v_add_u32_e32 v92, 0x19b40, v92
	v_add_f32_e32 v88, v88, v89
	v_add_f32_e32 v90, v90, v91
	ds_write_b32 v92, v88
	ds_write_b32 v93, v90
; __device__ __forceinline__ u16 f2bf(float f) { return (u16)(pk2(f, 0.f) & 0xffffu); }
; __device__ __forceinline__ float bf2f(u16 v) { return __uint_as_float(((unsigned)v) << 16); }
; __device__ __forceinline__ float fsigmoid(float x) { return __builtin_amdgcn_rcpf(1.0f + __expf(-x)); }
; __device__ __forceinline__ float row16_sum(float v) { v += dppf<0xB1>(v); v += dppf<0x4E>(v); v += dppf<0x141>(v); v += dppf<0x140>(v); return v; }
; __device__ unsigned long long rwkv2_phase(const Params& p, unsigned char* smem) {
;     ...
;                     float kmq[4], vq[4];
; #pragma unroll
;                     for (int r = 0; r < 4; ++r) { const int t = 4 * lq + r;
;                         const float rr = bf2f(raw[(0 * 17 + t + 1) * 64 + k]), rp_ = bf2f(raw[(0 * 17 + t) * 64 + k]);
;                         const float kr_ = bf2f(raw[(1 * 17 + t + 1) * 64 + k]), kp = bf2f(raw[(1 * 17 + t) * 64 + k]);
;                         const float vr = bf2f(raw[(2 * 17 + t + 1) * 64 + k]), vp = bf2f(raw[(2 * 17 + t) * 64 + k]);
;                         const float r_ = rr + (rp_ - rr) * mu_r, kx0 = kr_ + (kp - kr_) * mu_k, v_ = vr + (vp - vr) * mu_v;
;                         a_[r] = fsigmoid(a0k + accA[r]); kkv[r] = kx0 * kkk;
;                         const float kmod = kx0 * (1.0f + (a_[r] - 1.0f) * kak);
;                         const float eT = __expf(cum[r]); eTi[r] = __builtin_amdgcn_rcpf(eT); eP[r] = __expf(cum[r] - ld[r]);
;                         const float ssp = row16_sum(kkv[r] * kkv[r]), bop = row16_sum(r_ * kmod * rkk);
;                         if (l15 == 0) { ssP[t * 4 + w4] = ssp; bonP[t * 4 + w4] = bop; }
;                         Rt[t * 72 + k] = f2bf(r_ * eT); kmq[r] = kmod * eTi[r]; Kt[t * 72 + k] = f2bf(kmq[r]);
;                         Vf[t * 64 + k] = v_; vq[r] = v_;
;                         au[r] = -kkv[r] * eP[r]; bu[r] = kkv[r] * a_[r] * eTi[r];
;                         if (t == 15) W15[k] = eT; }
.LBB0_986:
	s_or_b64 exec, exec, s[28:29]
	v_mul_f32_e32 v88, 0x3fb8aa3b, v43
	v_exp_f32_e32 v88, v88
	v_lshlrev_b32_e32 v83, 16, v83
	v_lshlrev_b32_e32 v56, 16, v56
	v_sub_f32_e32 v56, v56, v83
	v_fmac_f32_e32 v83, v61, v56
	v_rcp_f32_e32 v56, v88
	v_mul_f32_e32 v85, v88, v85
	v_cvt_pk_bf16_f32 v88, v85, v2
	v_mad_u64_u32 v[84:85], s[28:29], v84, s52, v[102:103]
	v_lshl_add_u32 v85, v84, 1, s68
	ds_write_b16 v85, v88 offset:42112
	v_mul_f32_e32 v84, v56, v87
	v_cvt_pk_bf16_f32 v87, v84, v2
	ds_write_b16 v85, v87 offset:46720
	v_or_b32_e32 v87, 2, v58
	v_lshl_add_u32 v86, v86, 2, s33
	v_lshl_or_b32 v90, v87, 6, v102
	ds_write_b32 v86, v83 offset:58240
	v_lshl_add_u32 v86, v87, 7, v152
	v_lshl_add_u32 v88, v90, 1, 0
	v_add_f32_e32 v48, v63, v48
	v_mov_b32_e32 v89, v192
	v_mov_b32_e32 v88, v193
	v_mov_b32_e32 v93, v194
	v_mov_b32_e32 v92, v195
	v_mov_b32_e32 v91, v196
	v_mov_b32_e32 v86, v197
	v_mul_f32_e32 v48, 0xbfb8aa3b, v48
	v_exp_f32_e32 v48, v48
	s_waitcnt lgkmcnt(5)
	v_lshlrev_b32_e32 v89, 16, v89
	s_waitcnt lgkmcnt(4)
	v_lshlrev_b32_e32 v88, 16, v88
	s_waitcnt lgkmcnt(0)
	v_lshlrev_b32_e32 v94, 16, v86
	v_sub_f32_e32 v86, v88, v89
	v_add_f32_e32 v48, 1.0, v48
	v_fmac_f32_e32 v89, v3, v86
	v_rcp_f32_e32 v86, v48
	v_lshlrev_b32_e32 v93, 16, v93
	v_sub_f32_e32 v48, v94, v93
	v_fmac_f32_e32 v93, v60, v48
	v_add_f32_e32 v48, -1.0, v86
	v_fma_f32 v48, v65, v48, 1.0
	v_mul_f32_e32 v88, v64, v93
	v_mul_f32_e32 v93, v48, v93
	v_mul_f32_e32 v95, v89, v93
	v_mul_f32_e32 v48, v88, v88
	v_mov_b32_e32 v94, 0
	v_mul_f32_e32 v96, v66, v95
	v_mov_b32_e32 v97, 0
	v_mov_b32_dpp v94, v48 quad_perm:[1,0,3,2] row_mask:0xf bank_mask:0xf
	v_fmac_f32_e32 v94, v88, v88
	v_mov_b32_dpp v97, v96 quad_perm:[1,0,3,2] row_mask:0xf bank_mask:0xf
	v_fmac_f32_e32 v97, v66, v95
	v_add_f32_dpp v48, v94, v94 quad_perm:[2,3,0,1] row_mask:0xf bank_mask:0xf bound_ctrl:1
	v_mov_b32_e32 v94, 0
	v_add_f32_dpp v95, v97, v97 quad_perm:[2,3,0,1] row_mask:0xf bank_mask:0xf bound_ctrl:1
	v_add_f32_dpp v48, v48, v48 row_half_mirror row_mask:0xf bank_mask:0xf bound_ctrl:1
	v_mov_b32_e32 v96, 0
	v_add_f32_dpp v95, v95, v95 row_half_mirror row_mask:0xf bank_mask:0xf bound_ctrl:1
	v_mov_b32_dpp v94, v48 row_mirror row_mask:0xf bank_mask:0xf
	s_nop 0
	v_mov_b32_dpp v96, v95 row_mirror row_mask:0xf bank_mask:0xf
	s_and_saveexec_b64 s[28:29], vcc
	s_cbranch_execz .LBB0_988
	s_lshl_b32 s56, s88, 2
	v_lshl_or_b32 v87, v87, 4, s56
	v_add_u32_e32 v87, 0, v87
	v_add_u32_e32 v97, 0x19c40, v87
	v_add_u32_e32 v87, 0x19b40, v87
	v_add_f32_e32 v48, v48, v94
	v_add_f32_e32 v95, v95, v96
	ds_write_b32 v87, v48
	ds_write_b32 v97, v95
.LBB0_988:
	s_or_b64 exec, exec, s[28:29]
	v_mul_f32_e32 v48, 0x3fb8aa3b, v44
	v_lshlrev_b32_e32 v87, 16, v92
	v_exp_f32_e32 v92, v48
	v_lshlrev_b32_e32 v48, 16, v91
	v_sub_f32_e32 v48, v48, v87
	v_fmac_f32_e32 v87, v61, v48
	v_rcp_f32_e32 v48, v92
	v_mul_f32_e32 v89, v92, v89
	v_add_f32_e32 v49, v63, v49
	v_cvt_pk_bf16_f32 v89, v89, v2
	v_lshl_add_u32 v90, v90, 2, s33
	v_mul_f32_e32 v49, 0xbfb8aa3b, v49
	ds_write_b16 v85, v89 offset:42256
	v_mul_f32_e32 v89, v48, v93
	v_cvt_pk_bf16_f32 v91, v89, v2
	ds_write_b32 v90, v87 offset:58240
	v_or_b32_e32 v90, 3, v58
	v_exp_f32_e32 v49, v49
	ds_write_b16 v85, v91 offset:46864
	v_lshl_or_b32 v91, v90, 6, v102
	v_lshl_add_u32 v92, v90, 7, v152
	v_lshl_add_u32 v58, v91, 1, 0
	v_mov_b32_e32 v93, v198
	v_mov_b32_e32 v95, v199
	v_mov_b32_e32 v96, v200
	v_mov_b32_e32 v94, v201
	v_mov_b32_e32 v58, v202
	v_mov_b32_e32 v92, v203
	v_add_f32_e32 v49, 1.0, v49
	v_rcp_f32_e32 v49, v49
	s_waitcnt lgkmcnt(5)
	v_lshlrev_b32_e32 v93, 16, v93
	s_waitcnt lgkmcnt(4)
	v_lshlrev_b32_e32 v95, 16, v95
	s_waitcnt lgkmcnt(3)
	v_lshlrev_b32_e32 v96, 16, v96
	s_waitcnt lgkmcnt(0)
	v_lshlrev_b32_e32 v92, 16, v92
	v_sub_f32_e32 v95, v95, v93
	v_fmac_f32_e32 v93, v3, v95
	v_sub_f32_e32 v92, v92, v96
	v_add_f32_e32 v95, -1.0, v49
	v_fmac_f32_e32 v96, v60, v92
	v_fma_f32 v95, v65, v95, 1.0
	v_mul_f32_e32 v95, v95, v96
	v_mul_f32_e32 v92, v64, v96
	v_mul_f32_e32 v98, v93, v95
	v_mul_f32_e32 v96, v92, v92
	v_mov_b32_e32 v97, 0
	v_mul_f32_e32 v99, v66, v98
	v_mov_b32_e32 v100, 0
	v_mov_b32_dpp v97, v96 quad_perm:[1,0,3,2] row_mask:0xf bank_mask:0xf
	v_fmac_f32_e32 v97, v92, v92
	v_mov_b32_dpp v100, v99 quad_perm:[1,0,3,2] row_mask:0xf bank_mask:0xf
	v_fmac_f32_e32 v100, v66, v98
	v_add_f32_dpp v96, v97, v97 quad_perm:[2,3,0,1] row_mask:0xf bank_mask:0xf bound_ctrl:1
	v_mov_b32_e32 v97, 0
	v_add_f32_dpp v98, v100, v100 quad_perm:[2,3,0,1] row_mask:0xf bank_mask:0xf bound_ctrl:1
	v_add_f32_dpp v96, v96, v96 row_half_mirror row_mask:0xf bank_mask:0xf bound_ctrl:1
	v_mov_b32_e32 v99, 0
	v_add_f32_dpp v98, v98, v98 row_half_mirror row_mask:0xf bank_mask:0xf bound_ctrl:1
	v_mov_b32_dpp v97, v96 row_mirror row_mask:0xf bank_mask:0xf
	s_nop 0
	v_mov_b32_dpp v99, v98 row_mirror row_mask:0xf bank_mask:0xf
	s_and_saveexec_b64 s[28:29], vcc
	s_cbranch_execz .LBB0_990
	s_lshl_b32 s56, s88, 2
	v_lshl_or_b32 v90, v90, 4, s56
	v_add_u32_e32 v90, 0, v90
	v_add_u32_e32 v100, 0x19c40, v90
	v_add_u32_e32 v90, 0x19b40, v90
	v_add_f32_e32 v96, v96, v97
	v_add_f32_e32 v98, v98, v99
	ds_write_b32 v90, v96
	ds_write_b32 v100, v98

; __device__ __forceinline__ unsigned pk2(float lo, float hi) { unsigned r; asm volatile("v_cvt_pk_bf16_f32 %0, %1, %2" : "=v"(r) : "v"(lo), "v"(hi)); return r; }
; __device__ __forceinline__ u16 f2bf(float f) { return (u16)(pk2(f, 0.f) & 0xffffu); }
; #define LBARW() do { if (PROBE_ROLE >= 0 && wave == PROBE_ROLE) { const unsigned long long tb_ = __builtin_amdgcn_s_memrealtime(); LBAR(); twait += __builtin_amdgcn_s_memrealtime() - tb_; } else { LBAR(); } } while (0)
; __device__ unsigned long long rwkv2_phase(const Params& p, unsigned char* smem) {
;     ...
;                 LBARW();
;                 if (prep) {
;                     float bq[4];
; #pragma unroll
;                     for (int r = 0; r < 4; ++r) { const int t = 4 * lq + r; const f32x4 s4 = *(const f32x4*)(ssP + t * 4);
;                         const float rinv = rsqrtf(fmaxf((s4[0] + s4[1]) + (s4[2] + s4[3]), 1e-24f));
;                         At[t * 72 + k] = f2bf(au[r] * rinv); bq[r] = bu[r] * rinv; Bt[t * 72 + k] = f2bf(bq[r]);
;                         if (w4 == 0 && l15 == 0) { const f32x4 b4 = *(const f32x4*)(bonP + t * 4); bonus[t] = (b4[0] + b4[1]) + (b4[2] + b4[3]); } }
;                     { u32x2 w_; w_.x = pk2(bq[0], bq[1]); w_.y = pk2(bq[2], bq[3]); *(u32x2*)(BKT + k * 32 + lq * 8) = w_; }
.LBB0_993:
	s_waitcnt lgkmcnt(0)
	s_barrier
	s_and_b64 vcc, exec, s[26:27]
	s_cbranch_vccnz .LBB0_962
	v_and_b32_e32 v42, -16, v73
	v_lshl_add_u32 v45, v42, 2, 0
	v_add_u32_e32 v43, 0x19b40, v45
	ds_read_b128 v[180:183], v43
	ds_read_b128 v[184:187], v43 offset:16
	ds_read_b128 v[188:191], v43 offset:32
	ds_read_b128 v[192:195], v43 offset:48
	ds_read_b128 v[196:199], v43 offset:256
	ds_read_b128 v[200:203], v43 offset:272
	ds_read_b128 v[204:207], v43 offset:288
	ds_read_b128 v[208:211], v43 offset:304
	s_waitcnt lgkmcnt(0)
	v_cmp_eq_u32_e32 vcc, 0, v75
	v_lshlrev_b32_e32 v43, 2, v74
	v_mov_b32_e32 v46, v180
	v_mov_b32_e32 v47, v181
	v_mov_b32_e32 v48, v182
	v_mov_b32_e32 v49, v183
	v_add_f32_e32 v44, v46, v47
	v_add_f32_e32 v46, v48, v49
	v_add_f32_e32 v44, v44, v46
	v_max_f32_e32 v44, 0x179abe15, v44
	v_rsq_f32_e32 v44, v44
	v_mad_u64_u32 v[46:47], s[26:27], v74, s50, v[102:103]
	s_and_b64 s[26:27], s[64:65], vcc
	v_mul_f32_e32 v47, v141, v44
	v_lshl_add_u32 v46, v46, 1, s68
	v_cvt_pk_bf16_f32 v47, v47, v2
	v_mul_f32_e32 v44, v140, v44
	ds_write_b16 v46, v47 offset:39808
	v_cvt_pk_bf16_f32 v47, v44, v2
	ds_write_b16 v46, v47 offset:44416
	s_and_saveexec_b64 s[28:29], s[26:27]
	s_cbranch_execz .LBB0_996
	v_add_u32_e32 v45, 0x19c40, v45
	v_mov_b32_e32 v46, v196
	v_mov_b32_e32 v47, v197
	v_mov_b32_e32 v48, v198
	v_mov_b32_e32 v49, v199
	v_mov_b32_e32 v56, v47
	v_mov_b32_e32 v57, v48
	v_mov_b32_e32 v47, v49
	v_pk_add_f32 v[46:47], v[56:57], v[46:47]
	s_nop 0
	v_add_f32_e32 v45, v46, v47
	v_lshl_add_u32 v46, v43, 2, s62
	ds_write_b32 v46, v45 offset:10496
.LBB0_996:
	s_or_b64 exec, exec, s[28:29]
	v_or_b32_e32 v47, 1, v43
	v_lshl_add_u32 v45, v47, 4, 0
	v_add_u32_e32 v45, 0x19b40, v45
	v_mad_u64_u32 v[48:49], s[28:29], v47, s52, v[102:103]
	v_mov_b32_e32 v56, v184
	v_mov_b32_e32 v57, v185
	v_mov_b32_e32 v58, v186
	v_mov_b32_e32 v59, v187
	v_add_f32_e32 v45, v56, v57
	v_add_f32_e32 v46, v58, v59
	v_add_f32_e32 v45, v45, v46
	v_max_f32_e32 v45, 0x179abe15, v45
	v_rsq_f32_e32 v45, v45
	v_lshl_add_u32 v46, v48, 1, s68
	v_mul_f32_e32 v48, v139, v45
	v_mul_f32_e32 v45, v138, v45
	v_cvt_pk_bf16_f32 v48, v48, v2
	ds_write_b16 v46, v48 offset:39808
	v_cvt_pk_bf16_f32 v48, v45, v2
	ds_write_b16 v46, v48 offset:44416
	s_and_saveexec_b64 s[28:29], s[26:27]
	s_cbranch_execz .LBB0_998
	v_lshlrev_b32_e32 v47, 2, v47
	v_lshl_add_u32 v47, v47, 2, 0
	v_add_u32_e32 v47, 0x19c40, v47
	v_mov_b32_e32 v56, v200
	v_mov_b32_e32 v57, v201
	v_mov_b32_e32 v58, v202
	v_mov_b32_e32 v59, v203
	v_mov_b32_e32 v48, v57
	v_mov_b32_e32 v49, v58
	v_mov_b32_e32 v57, v59
	v_pk_add_f32 v[48:49], v[48:49], v[56:57]
	s_nop 0
	v_add_f32_e32 v47, v48, v49
	v_lshl_add_u32 v48, v43, 2, s62
	ds_write_b32 v48, v47 offset:10500
.LBB0_998:
	s_or_b64 exec, exec, s[28:29]
	v_or_b32_e32 v48, 2, v43
	v_lshl_add_u32 v47, v48, 4, 0
	v_add_u32_e32 v47, 0x19b40, v47
	v_mov_b32_e32 v56, v188
	v_mov_b32_e32 v57, v189
	v_mov_b32_e32 v58, v190
	v_mov_b32_e32 v59, v191
	v_add_f32_e32 v47, v56, v57
	v_add_f32_e32 v49, v58, v59
	v_add_f32_e32 v47, v47, v49
	v_max_f32_e32 v47, 0x179abe15, v47
	v_rsq_f32_e32 v47, v47
	s_nop 0
	v_mul_f32_e32 v49, v137, v47
	v_mul_f32_e32 v47, v136, v47
	v_cvt_pk_bf16_f32 v49, v49, v2
	ds_write_b16 v46, v49 offset:39952
	v_cvt_pk_bf16_f32 v49, v47, v2
	ds_write_b16 v46, v49 offset:44560
	s_and_saveexec_b64 s[28:29], s[26:27]
	s_cbranch_execz .LBB0_1000
	v_lshlrev_b32_e32 v48, 2, v48
	v_lshl_add_u32 v48, v48, 2, 0
	v_add_u32_e32 v48, 0x19c40, v48
	v_mov_b32_e32 v56, v204
	v_mov_b32_e32 v57, v205
	v_mov_b32_e32 v58, v206
	v_mov_b32_e32 v59, v207
	v_mov_b32_e32 v48, v57
	v_mov_b32_e32 v49, v58
	v_mov_b32_e32 v57, v59
	v_pk_add_f32 v[48:49], v[48:49], v[56:57]
	s_nop 0
	v_add_f32_e32 v48, v48, v49
	v_lshl_add_u32 v49, v43, 2, s62
	ds_write_b32 v49, v48 offset:10504
.LBB0_1000:
	s_or_b64 exec, exec, s[28:29]
	v_or_b32_e32 v49, 3, v43
	v_lshl_add_u32 v48, v49, 4, 0
	v_add_u32_e32 v48, 0x19b40, v48
	v_mov_b32_e32 v56, v192
	v_mov_b32_e32 v57, v193
	v_mov_b32_e32 v58, v194
	v_mov_b32_e32 v59, v195
	v_add_f32_e32 v48, v56, v57
	v_add_f32_e32 v56, v58, v59
	v_add_f32_e32 v48, v48, v56
	v_max_f32_e32 v48, 0x179abe15, v48
	v_rsq_f32_e32 v48, v48
	s_nop 0
	v_mul_f32_e32 v56, v135, v48
	v_mul_f32_e32 v48, v134, v48
	v_cvt_pk_bf16_f32 v56, v56, v2
	ds_write_b16 v46, v56 offset:40096
	v_cvt_pk_bf16_f32 v56, v48, v2
	ds_write_b16 v46, v56 offset:44704
	s_and_saveexec_b64 s[28:29], s[26:27]
	s_cbranch_execz .LBB0_961
	v_lshlrev_b32_e32 v46, 2, v49
	v_lshl_add_u32 v46, v46, 2, 0
	v_add_u32_e32 v46, 0x19c40, v46
	v_lshl_add_u32 v43, v43, 2, s62
	v_mov_b32_e32 v56, v208
	v_mov_b32_e32 v57, v209
	v_mov_b32_e32 v58, v210
	v_mov_b32_e32 v59, v211
	v_mov_b32_e32 v74, v57
	v_mov_b32_e32 v75, v58
	v_mov_b32_e32 v57, v59
	v_pk_add_f32 v[56:57], v[74:75], v[56:57]
	s_nop 0
	v_add_f32_e32 v46, v56, v57
	ds_write_b32 v43, v46 offset:10508
	s_branch .LBB0_961
